# GU/in-proj K-loop: half-unit branch test moved in front of the opening barrier (loop-edge edit: no branch between barrier release and the first MFMA)
# baseline (speedup 1.0000x reference)
; #define PG8_STAGE(bufoff, gbase, voff) do { _Pragma("unroll") for (int _i = 0; _i < 2; ++_i) \
;         __builtin_amdgcn_global_load_lds((const unsigned*)((const char*)(gbase) + (voff)[_i]), (PG8_LAS unsigned*)(lds + (bufoff) + ldsw + _i * 8192), 16, 0, 0); } while (0)
; #define PG8_LDA(dst, b, h) do { _Pragma("unroll") for (int m = 0; m < 4; ++m) _Pragma("unroll") for (int k = 0; k < 2; ++k) dst[m][k] = *(const PG8_LAS bf16x8*)(lds + PG8_SA(b, h) + aoff + m * 2048 + k * 1024); } while (0)
; #define PG8_MMA(ai, bj, At, Bt) do { __builtin_amdgcn_s_setprio(1); _Pragma("unroll") for (int m = 0; m < 4; ++m) _Pragma("unroll") for (int n = 0; n < 2; ++n) _Pragma("unroll") for (int k = 0; k < 2; ++k) \
;         acc[ai][bj][m][n] = __builtin_amdgcn_mfma_f32_16x16x32_bf16(Bt[n][k], At[m][k], acc[ai][bj][m][n], 0, 0, 0); __builtin_amdgcn_s_setprio(0); } while (0)
; #define PG8_WAIT_V(n) asm volatile("s_waitcnt vmcnt(" #n ")" ::: "memory")
; #define PG8_WAIT_L(n) asm volatile("s_waitcnt lgkmcnt(" #n ")" ::: "memory")
; #define PG8_BAR __builtin_amdgcn_s_barrier()
; #define PG8_SCHED __builtin_amdgcn_sched_barrier(0)
; template <class Epi, class Sched, bool ALIGN_EPI = false, bool SP2 = false>
; __device__ __forceinline__ void gemm_phase(PG8_LAS unsigned char* lds, const Gemm g, const Sched& S, const Epi& E) {
;     ...
;             if (full) PG8_LDA(At, 0, 1); PG8_STAGE(PG8_SB(0, 0), b2, voffB); PG8_STAGE(PG8_SB(0, 1), b2 + hstep, voffB); PG8_STAGE(PG8_SA(0, 0), a2, voffA);
;             PG8_WAIT_V(8); PG8_WAIT_L(0); PG8_BAR; if (full) { PG8_MMA(1, 0, At, B0); PG8_MMA(1, 1, At, B1); } PG8_BAR; PG8_SCHED;
.LBB0_294:
	s_add_u32 s38, s36, 0xfffc0080
	s_addc_u32 s39, s37, -1
	s_cmp_eq_u32 s89, 12
	s_cselect_b32 s43, s23, s39
	s_cselect_b32 s42, s81, s38
	s_cselect_b32 s39, s21, s88
	s_cselect_b32 s38, s82, s83
	s_mov_b32 m0, s54
	v_lshl_add_u64 v[2:3], s[38:39], 0, v[198:199]
	s_add_u32 s90, s38, 0x40000
	global_load_lds_dwordx4 v[2:3], off
	v_lshl_add_u64 v[208:209], s[38:39], 0, v[202:203]
	s_mov_b32 m0, s55
	s_addc_u32 s91, s39, 0
	global_load_lds_dwordx4 v[208:209], off
	v_lshl_add_u64 v[210:211], s[90:91], 0, v[198:199]
	s_mov_b32 m0, s56
	v_lshl_add_u64 v[220:221], s[42:43], 0, v[200:201]
	global_load_lds_dwordx4 v[210:211], off
	v_lshl_add_u64 v[210:211], s[90:91], 0, v[202:203]
	s_mov_b32 m0, s57
	s_and_b64 vcc, exec, s[4:5]
	global_load_lds_dwordx4 v[210:211], off
	v_lshl_add_u64 v[210:211], s[42:43], 0, v[196:197]
	s_mov_b32 m0, s31
	s_nop 0
	global_load_lds_dwordx4 v[210:211], off
	s_mov_b32 m0, s58
	s_nop 0
	global_load_lds_dwordx4 v[220:221], off
	s_waitcnt vmcnt(8)
	s_waitcnt lgkmcnt(0)
	s_setprio 1
	s_cbranch_vccnz .Lmy_skipa1
	s_barrier
	v_mfma_f32_16x16x32_bf16 v[64:67], v[148:151], v[176:179], v[64:67]
	v_mfma_f32_16x16x32_bf16 v[56:59], v[156:159], v[176:179], v[56:59]
	v_mfma_f32_16x16x32_bf16 v[48:51], v[148:151], v[172:175], v[48:51]
	v_mfma_f32_16x16x32_bf16 v[40:43], v[156:159], v[172:175], v[40:43]
	v_mfma_f32_16x16x32_bf16 v[32:35], v[148:151], v[168:171], v[32:35]
	v_mfma_f32_16x16x32_bf16 v[24:27], v[156:159], v[168:171], v[24:27]
	v_mfma_f32_16x16x32_bf16 v[16:19], v[148:151], v[164:167], v[16:19]
	v_mfma_f32_16x16x32_bf16 v[8:11], v[156:159], v[164:167], v[8:11]
	v_mfma_f32_16x16x32_bf16 v[64:67], v[152:155], v[192:195], v[64:67]
	v_mfma_f32_16x16x32_bf16 v[56:59], v[160:163], v[192:195], v[56:59]
	v_mfma_f32_16x16x32_bf16 v[48:51], v[152:155], v[188:191], v[48:51]
	v_mfma_f32_16x16x32_bf16 v[40:43], v[160:163], v[188:191], v[40:43]
	v_mfma_f32_16x16x32_bf16 v[32:35], v[152:155], v[184:187], v[32:35]
	v_mfma_f32_16x16x32_bf16 v[24:27], v[160:163], v[184:187], v[24:27]
	v_mfma_f32_16x16x32_bf16 v[16:19], v[152:155], v[180:183], v[16:19]
	v_mfma_f32_16x16x32_bf16 v[8:11], v[160:163], v[180:183], v[8:11]
	v_mfma_f32_16x16x32_bf16 v[60:63], v[132:135], v[176:179], v[60:63]
	v_mfma_f32_16x16x32_bf16 v[52:55], v[140:143], v[176:179], v[52:55]
	v_mfma_f32_16x16x32_bf16 v[44:47], v[132:135], v[172:175], v[44:47]
	v_mfma_f32_16x16x32_bf16 v[36:39], v[140:143], v[172:175], v[36:39]
	v_mfma_f32_16x16x32_bf16 v[28:31], v[132:135], v[168:171], v[28:31]
	v_mfma_f32_16x16x32_bf16 v[20:23], v[140:143], v[168:171], v[20:23]
	v_mfma_f32_16x16x32_bf16 v[12:15], v[132:135], v[164:167], v[12:15]
	v_mfma_f32_16x16x32_bf16 v[4:7], v[140:143], v[164:167], v[4:7]
	v_mfma_f32_16x16x32_bf16 v[60:63], v[136:139], v[192:195], v[60:63]
	v_mfma_f32_16x16x32_bf16 v[52:55], v[144:147], v[192:195], v[52:55]
	v_mfma_f32_16x16x32_bf16 v[44:47], v[136:139], v[188:191], v[44:47]
	v_mfma_f32_16x16x32_bf16 v[36:39], v[144:147], v[188:191], v[36:39]
	v_mfma_f32_16x16x32_bf16 v[28:31], v[136:139], v[184:187], v[28:31]
	v_mfma_f32_16x16x32_bf16 v[20:23], v[144:147], v[184:187], v[20:23]
	v_mfma_f32_16x16x32_bf16 v[12:15], v[136:139], v[180:183], v[12:15]
	v_mfma_f32_16x16x32_bf16 v[4:7], v[144:147], v[180:183], v[4:7]

; #define PG8_STAGE(bufoff, gbase, voff) do { _Pragma("unroll") for (int _i = 0; _i < 2; ++_i) \
;         __builtin_amdgcn_global_load_lds((const unsigned*)((const char*)(gbase) + (voff)[_i]), (PG8_LAS unsigned*)(lds + (bufoff) + ldsw + _i * 8192), 16, 0, 0); } while (0)
; #define PG8_LDA(dst, b, h) do { _Pragma("unroll") for (int m = 0; m < 4; ++m) _Pragma("unroll") for (int k = 0; k < 2; ++k) dst[m][k] = *(const PG8_LAS bf16x8*)(lds + PG8_SA(b, h) + aoff + m * 2048 + k * 1024); } while (0)
; #define PG8_MMA(ai, bj, At, Bt) do { __builtin_amdgcn_s_setprio(1); _Pragma("unroll") for (int m = 0; m < 4; ++m) _Pragma("unroll") for (int n = 0; n < 2; ++n) _Pragma("unroll") for (int k = 0; k < 2; ++k) \
;         acc[ai][bj][m][n] = __builtin_amdgcn_mfma_f32_16x16x32_bf16(Bt[n][k], At[m][k], acc[ai][bj][m][n], 0, 0, 0); __builtin_amdgcn_s_setprio(0); } while (0)
; #define PG8_WAIT_V(n) asm volatile("s_waitcnt vmcnt(" #n ")" ::: "memory")
; #define PG8_WAIT_L(n) asm volatile("s_waitcnt lgkmcnt(" #n ")" ::: "memory")
; #define PG8_BAR __builtin_amdgcn_s_barrier()
; #define PG8_SCHED __builtin_amdgcn_sched_barrier(0)
; template <class Epi, class Sched, bool ALIGN_EPI = false, bool SP2 = false>
; __device__ __forceinline__ void gemm_phase(PG8_LAS unsigned char* lds, const Gemm g, const Sched& S, const Epi& E) {
;     ...
;             if (full) PG8_LDA(At, 1, 1); PG8_STAGE(PG8_SB(1, 0), b3, voffB); PG8_STAGE(PG8_SB(1, 1), b3 + hstep, voffB); PG8_STAGE(PG8_SA(1, 0), a3, voffA);
;             PG8_WAIT_V(8); PG8_WAIT_L(0); PG8_BAR; if (full) { PG8_MMA(1, 0, At, B0); PG8_MMA(1, 1, At, B1); } PG8_BAR; PG8_SCHED;
.LBB0_298:
	s_mov_b32 m0, s61
	v_lshl_add_u64 v[2:3], v[2:3], 0, s[52:53]
	s_add_u32 s38, s38, 0x40080
	global_load_lds_dwordx4 v[2:3], off
	v_lshl_add_u64 v[2:3], v[208:209], 0, s[52:53]
	s_mov_b32 m0, s62
	s_addc_u32 s39, s39, 0
	global_load_lds_dwordx4 v[2:3], off
	v_lshl_add_u64 v[2:3], s[38:39], 0, v[198:199]
	s_mov_b32 m0, s65
	s_and_b64 vcc, exec, s[4:5]
	global_load_lds_dwordx4 v[2:3], off
	v_lshl_add_u64 v[2:3], s[38:39], 0, v[202:203]
	s_mov_b32 m0, s68
	s_nop 0
	global_load_lds_dwordx4 v[2:3], off
	v_lshl_add_u64 v[2:3], v[210:211], 0, s[52:53]
	s_mov_b32 m0, s63
	s_nop 0
	global_load_lds_dwordx4 v[2:3], off
	v_lshl_add_u64 v[2:3], v[220:221], 0, s[52:53]
	s_mov_b32 m0, s64
	s_nop 0
	global_load_lds_dwordx4 v[2:3], off
	s_waitcnt vmcnt(8)
	s_waitcnt lgkmcnt(0)
	s_setprio 1
	s_cbranch_vccnz .Lmy_skipa2
	s_barrier
	v_mfma_f32_16x16x32_bf16 v[64:67], v[148:151], v[176:179], v[64:67]
	v_mfma_f32_16x16x32_bf16 v[56:59], v[156:159], v[176:179], v[56:59]
	v_mfma_f32_16x16x32_bf16 v[48:51], v[148:151], v[172:175], v[48:51]
	v_mfma_f32_16x16x32_bf16 v[40:43], v[156:159], v[172:175], v[40:43]
	v_mfma_f32_16x16x32_bf16 v[32:35], v[148:151], v[168:171], v[32:35]
	v_mfma_f32_16x16x32_bf16 v[24:27], v[156:159], v[168:171], v[24:27]
	v_mfma_f32_16x16x32_bf16 v[16:19], v[148:151], v[164:167], v[16:19]
	v_mfma_f32_16x16x32_bf16 v[8:11], v[156:159], v[164:167], v[8:11]
	v_mfma_f32_16x16x32_bf16 v[64:67], v[152:155], v[192:195], v[64:67]
	v_mfma_f32_16x16x32_bf16 v[56:59], v[160:163], v[192:195], v[56:59]
	v_mfma_f32_16x16x32_bf16 v[48:51], v[152:155], v[188:191], v[48:51]
	v_mfma_f32_16x16x32_bf16 v[40:43], v[160:163], v[188:191], v[40:43]
	v_mfma_f32_16x16x32_bf16 v[32:35], v[152:155], v[184:187], v[32:35]
	v_mfma_f32_16x16x32_bf16 v[24:27], v[160:163], v[184:187], v[24:27]
	v_mfma_f32_16x16x32_bf16 v[16:19], v[152:155], v[180:183], v[16:19]
	v_mfma_f32_16x16x32_bf16 v[8:11], v[160:163], v[180:183], v[8:11]
	v_mfma_f32_16x16x32_bf16 v[60:63], v[132:135], v[176:179], v[60:63]
	v_mfma_f32_16x16x32_bf16 v[52:55], v[140:143], v[176:179], v[52:55]
	v_mfma_f32_16x16x32_bf16 v[44:47], v[132:135], v[172:175], v[44:47]
	v_mfma_f32_16x16x32_bf16 v[36:39], v[140:143], v[172:175], v[36:39]
	v_mfma_f32_16x16x32_bf16 v[28:31], v[132:135], v[168:171], v[28:31]
	v_mfma_f32_16x16x32_bf16 v[20:23], v[140:143], v[168:171], v[20:23]
	v_mfma_f32_16x16x32_bf16 v[12:15], v[132:135], v[164:167], v[12:15]
	v_mfma_f32_16x16x32_bf16 v[2:5], v[140:143], v[164:167], v[4:7]
	v_mfma_f32_16x16x32_bf16 v[60:63], v[136:139], v[192:195], v[60:63]
	v_mfma_f32_16x16x32_bf16 v[52:55], v[144:147], v[192:195], v[52:55]
	v_mfma_f32_16x16x32_bf16 v[44:47], v[136:139], v[188:191], v[44:47]
	v_mfma_f32_16x16x32_bf16 v[36:39], v[144:147], v[188:191], v[36:39]
	v_mfma_f32_16x16x32_bf16 v[28:31], v[136:139], v[184:187], v[28:31]
	v_mfma_f32_16x16x32_bf16 v[20:23], v[144:147], v[184:187], v[20:23]
	v_mfma_f32_16x16x32_bf16 v[12:15], v[136:139], v[180:183], v[12:15]
	v_mfma_f32_16x16x32_bf16 v[4:7], v[144:147], v[180:183], v[2:5]
	s_branch .LBB0_291
.Lmy_skipa1:
	s_barrier
	s_branch .LBB0_296

; #define PG8_STAGE(bufoff, gbase, voff) do { _Pragma("unroll") for (int _i = 0; _i < 2; ++_i) \
;         __builtin_amdgcn_global_load_lds((const unsigned*)((const char*)(gbase) + (voff)[_i]), (PG8_LAS unsigned*)(lds + (bufoff) + ldsw + _i * 8192), 16, 0, 0); } while (0)
; #define PG8_LDA(dst, b, h) do { _Pragma("unroll") for (int m = 0; m < 4; ++m) _Pragma("unroll") for (int k = 0; k < 2; ++k) dst[m][k] = *(const PG8_LAS bf16x8*)(lds + PG8_SA(b, h) + aoff + m * 2048 + k * 1024); } while (0)
; #define PG8_MMA(ai, bj, At, Bt) do { __builtin_amdgcn_s_setprio(1); _Pragma("unroll") for (int m = 0; m < 4; ++m) _Pragma("unroll") for (int n = 0; n < 2; ++n) _Pragma("unroll") for (int k = 0; k < 2; ++k) \
;         acc[ai][bj][m][n] = __builtin_amdgcn_mfma_f32_16x16x32_bf16(Bt[n][k], At[m][k], acc[ai][bj][m][n], 0, 0, 0); __builtin_amdgcn_s_setprio(0); } while (0)
; #define PG8_WAIT_V(n) asm volatile("s_waitcnt vmcnt(" #n ")" ::: "memory")
; #define PG8_WAIT_L(n) asm volatile("s_waitcnt lgkmcnt(" #n ")" ::: "memory")
; #define PG8_BAR __builtin_amdgcn_s_barrier()
; #define PG8_SCHED __builtin_amdgcn_sched_barrier(0)
; template <class Epi, class Sched, bool ALIGN_EPI = false, bool SP2 = false>
; __device__ __forceinline__ void gemm_phase(PG8_LAS unsigned char* lds, const Gemm g, const Sched& S, const Epi& E) {
;     ...
;             if (full) PG8_LDA(At, 0, 1); PG8_STAGE(PG8_SB(0, 0), b2, voffB); PG8_STAGE(PG8_SB(0, 1), b2 + hstep, voffB); PG8_STAGE(PG8_SA(0, 0), a2, voffA);
;             PG8_WAIT_V(8); PG8_WAIT_L(0); PG8_BAR; if (full) { PG8_MMA(1, 0, At, B0); PG8_MMA(1, 1, At, B1); } PG8_BAR; PG8_SCHED;
.LBB0_523:
	s_add_u32 s36, s34, 0xfffc0080
	s_addc_u32 s37, s35, -1
	s_cmp_eq_u32 s82, 12
	s_cselect_b32 s39, s1, s37
	s_cselect_b32 s38, s19, s36
	s_cselect_b32 s37, s17, s81
	s_cselect_b32 s36, s29, s80
	s_mov_b32 m0, s49
	v_lshl_add_u64 v[2:3], s[36:37], 0, v[198:199]
	s_add_u32 s88, s36, 0x40000
	global_load_lds_dwordx4 v[2:3], off
	v_lshl_add_u64 v[208:209], s[36:37], 0, v[202:203]
	s_mov_b32 m0, s54
	s_addc_u32 s89, s37, 0
	global_load_lds_dwordx4 v[208:209], off
	v_lshl_add_u64 v[210:211], s[88:89], 0, v[198:199]
	s_mov_b32 m0, s55
	v_lshl_add_u64 v[220:221], s[38:39], 0, v[200:201]
	global_load_lds_dwordx4 v[210:211], off
	v_lshl_add_u64 v[210:211], s[88:89], 0, v[202:203]
	s_mov_b32 m0, s56
	s_and_b64 vcc, exec, s[4:5]
	global_load_lds_dwordx4 v[210:211], off
	v_lshl_add_u64 v[210:211], s[38:39], 0, v[196:197]
	s_mov_b32 m0, s27
	s_nop 0
	global_load_lds_dwordx4 v[210:211], off
	s_mov_b32 m0, s57
	s_nop 0
	global_load_lds_dwordx4 v[220:221], off
	s_waitcnt vmcnt(8)
	s_waitcnt lgkmcnt(0)
	s_setprio 1
	s_cbranch_vccnz .Lmy_skipb1
	s_barrier
	v_mfma_f32_16x16x32_bf16 v[64:67], v[148:151], v[176:179], v[64:67]
	v_mfma_f32_16x16x32_bf16 v[60:63], v[156:159], v[176:179], v[60:63]
	v_mfma_f32_16x16x32_bf16 v[48:51], v[148:151], v[172:175], v[48:51]
	v_mfma_f32_16x16x32_bf16 v[44:47], v[156:159], v[172:175], v[44:47]
	v_mfma_f32_16x16x32_bf16 v[32:35], v[148:151], v[168:171], v[32:35]
	v_mfma_f32_16x16x32_bf16 v[28:31], v[156:159], v[168:171], v[28:31]
	v_mfma_f32_16x16x32_bf16 v[16:19], v[148:151], v[164:167], v[16:19]
	v_mfma_f32_16x16x32_bf16 v[12:15], v[156:159], v[164:167], v[12:15]
	v_mfma_f32_16x16x32_bf16 v[64:67], v[152:155], v[192:195], v[64:67]
	v_mfma_f32_16x16x32_bf16 v[60:63], v[160:163], v[192:195], v[60:63]
	v_mfma_f32_16x16x32_bf16 v[48:51], v[152:155], v[188:191], v[48:51]
	v_mfma_f32_16x16x32_bf16 v[44:47], v[160:163], v[188:191], v[44:47]
	v_mfma_f32_16x16x32_bf16 v[32:35], v[152:155], v[184:187], v[32:35]
	v_mfma_f32_16x16x32_bf16 v[28:31], v[160:163], v[184:187], v[28:31]
	v_mfma_f32_16x16x32_bf16 v[16:19], v[152:155], v[180:183], v[16:19]
	v_mfma_f32_16x16x32_bf16 v[12:15], v[160:163], v[180:183], v[12:15]
	v_mfma_f32_16x16x32_bf16 v[56:59], v[132:135], v[176:179], v[56:59]
	v_mfma_f32_16x16x32_bf16 v[52:55], v[140:143], v[176:179], v[52:55]
	v_mfma_f32_16x16x32_bf16 v[40:43], v[132:135], v[172:175], v[40:43]
	v_mfma_f32_16x16x32_bf16 v[36:39], v[140:143], v[172:175], v[36:39]
	v_mfma_f32_16x16x32_bf16 v[24:27], v[132:135], v[168:171], v[24:27]
	v_mfma_f32_16x16x32_bf16 v[20:23], v[140:143], v[168:171], v[20:23]
	v_mfma_f32_16x16x32_bf16 v[8:11], v[132:135], v[164:167], v[8:11]
	v_mfma_f32_16x16x32_bf16 v[4:7], v[140:143], v[164:167], v[4:7]
	v_mfma_f32_16x16x32_bf16 v[56:59], v[136:139], v[192:195], v[56:59]
	v_mfma_f32_16x16x32_bf16 v[52:55], v[144:147], v[192:195], v[52:55]
	v_mfma_f32_16x16x32_bf16 v[40:43], v[136:139], v[188:191], v[40:43]
	v_mfma_f32_16x16x32_bf16 v[36:39], v[144:147], v[188:191], v[36:39]
	v_mfma_f32_16x16x32_bf16 v[24:27], v[136:139], v[184:187], v[24:27]
	v_mfma_f32_16x16x32_bf16 v[20:23], v[144:147], v[184:187], v[20:23]
	v_mfma_f32_16x16x32_bf16 v[8:11], v[136:139], v[180:183], v[8:11]
	v_mfma_f32_16x16x32_bf16 v[4:7], v[144:147], v[180:183], v[4:7]

; #define PG8_STAGE(bufoff, gbase, voff) do { _Pragma("unroll") for (int _i = 0; _i < 2; ++_i) \
;         __builtin_amdgcn_global_load_lds((const unsigned*)((const char*)(gbase) + (voff)[_i]), (PG8_LAS unsigned*)(lds + (bufoff) + ldsw + _i * 8192), 16, 0, 0); } while (0)
; #define PG8_LDA(dst, b, h) do { _Pragma("unroll") for (int m = 0; m < 4; ++m) _Pragma("unroll") for (int k = 0; k < 2; ++k) dst[m][k] = *(const PG8_LAS bf16x8*)(lds + PG8_SA(b, h) + aoff + m * 2048 + k * 1024); } while (0)
; #define PG8_MMA(ai, bj, At, Bt) do { __builtin_amdgcn_s_setprio(1); _Pragma("unroll") for (int m = 0; m < 4; ++m) _Pragma("unroll") for (int n = 0; n < 2; ++n) _Pragma("unroll") for (int k = 0; k < 2; ++k) \
;         acc[ai][bj][m][n] = __builtin_amdgcn_mfma_f32_16x16x32_bf16(Bt[n][k], At[m][k], acc[ai][bj][m][n], 0, 0, 0); __builtin_amdgcn_s_setprio(0); } while (0)
; #define PG8_WAIT_V(n) asm volatile("s_waitcnt vmcnt(" #n ")" ::: "memory")
; #define PG8_WAIT_L(n) asm volatile("s_waitcnt lgkmcnt(" #n ")" ::: "memory")
; #define PG8_BAR __builtin_amdgcn_s_barrier()
; #define PG8_SCHED __builtin_amdgcn_sched_barrier(0)
; template <class Epi, class Sched, bool ALIGN_EPI = false, bool SP2 = false>
; __device__ __forceinline__ void gemm_phase(PG8_LAS unsigned char* lds, const Gemm g, const Sched& S, const Epi& E) {
;     ...
;             if (full) PG8_LDA(At, 1, 1); PG8_STAGE(PG8_SB(1, 0), b3, voffB); PG8_STAGE(PG8_SB(1, 1), b3 + hstep, voffB); PG8_STAGE(PG8_SA(1, 0), a3, voffA);
;             PG8_WAIT_V(8); PG8_WAIT_L(0); PG8_BAR; if (full) { PG8_MMA(1, 0, At, B0); PG8_MMA(1, 1, At, B1); } PG8_BAR; PG8_SCHED;
.LBB0_527:
	s_mov_b32 m0, s62
	v_lshl_add_u64 v[2:3], v[2:3], 0, s[52:53]
	s_add_u32 s36, s36, 0x40080
	global_load_lds_dwordx4 v[2:3], off
	v_lshl_add_u64 v[2:3], v[208:209], 0, s[52:53]
	s_mov_b32 m0, s63
	s_addc_u32 s37, s37, 0
	global_load_lds_dwordx4 v[2:3], off
	v_lshl_add_u64 v[2:3], s[36:37], 0, v[198:199]
	s_mov_b32 m0, s68
	s_and_b64 vcc, exec, s[4:5]
	global_load_lds_dwordx4 v[2:3], off
	v_lshl_add_u64 v[2:3], s[36:37], 0, v[202:203]
	s_mov_b32 m0, s69
	s_nop 0
	global_load_lds_dwordx4 v[2:3], off
	v_lshl_add_u64 v[2:3], v[210:211], 0, s[52:53]
	s_mov_b32 m0, s64
	s_nop 0
	global_load_lds_dwordx4 v[2:3], off
	v_lshl_add_u64 v[2:3], v[220:221], 0, s[52:53]
	s_mov_b32 m0, s65
	s_nop 0
	global_load_lds_dwordx4 v[2:3], off
	s_waitcnt vmcnt(8)
	s_waitcnt lgkmcnt(0)
	s_setprio 1
	s_cbranch_vccnz .Lmy_skipb2
	s_barrier
	v_mfma_f32_16x16x32_bf16 v[64:67], v[148:151], v[176:179], v[64:67]
	v_mfma_f32_16x16x32_bf16 v[60:63], v[156:159], v[176:179], v[60:63]
	v_mfma_f32_16x16x32_bf16 v[48:51], v[148:151], v[172:175], v[48:51]
	v_mfma_f32_16x16x32_bf16 v[44:47], v[156:159], v[172:175], v[44:47]
	v_mfma_f32_16x16x32_bf16 v[32:35], v[148:151], v[168:171], v[32:35]
	v_mfma_f32_16x16x32_bf16 v[28:31], v[156:159], v[168:171], v[28:31]
	v_mfma_f32_16x16x32_bf16 v[16:19], v[148:151], v[164:167], v[16:19]
	v_mfma_f32_16x16x32_bf16 v[12:15], v[156:159], v[164:167], v[12:15]
	v_mfma_f32_16x16x32_bf16 v[64:67], v[152:155], v[192:195], v[64:67]
	v_mfma_f32_16x16x32_bf16 v[60:63], v[160:163], v[192:195], v[60:63]
	v_mfma_f32_16x16x32_bf16 v[48:51], v[152:155], v[188:191], v[48:51]
	v_mfma_f32_16x16x32_bf16 v[44:47], v[160:163], v[188:191], v[44:47]
	v_mfma_f32_16x16x32_bf16 v[32:35], v[152:155], v[184:187], v[32:35]
	v_mfma_f32_16x16x32_bf16 v[28:31], v[160:163], v[184:187], v[28:31]
	v_mfma_f32_16x16x32_bf16 v[16:19], v[152:155], v[180:183], v[16:19]
	v_mfma_f32_16x16x32_bf16 v[12:15], v[160:163], v[180:183], v[12:15]
	v_mfma_f32_16x16x32_bf16 v[56:59], v[132:135], v[176:179], v[56:59]
	v_mfma_f32_16x16x32_bf16 v[52:55], v[140:143], v[176:179], v[52:55]
	v_mfma_f32_16x16x32_bf16 v[40:43], v[132:135], v[172:175], v[40:43]
	v_mfma_f32_16x16x32_bf16 v[36:39], v[140:143], v[172:175], v[36:39]
	v_mfma_f32_16x16x32_bf16 v[24:27], v[132:135], v[168:171], v[24:27]
	v_mfma_f32_16x16x32_bf16 v[20:23], v[140:143], v[168:171], v[20:23]
	v_mfma_f32_16x16x32_bf16 v[8:11], v[132:135], v[164:167], v[8:11]
	v_mfma_f32_16x16x32_bf16 v[2:5], v[140:143], v[164:167], v[4:7]
	v_mfma_f32_16x16x32_bf16 v[56:59], v[136:139], v[192:195], v[56:59]
	v_mfma_f32_16x16x32_bf16 v[52:55], v[144:147], v[192:195], v[52:55]
	v_mfma_f32_16x16x32_bf16 v[40:43], v[136:139], v[188:191], v[40:43]
	v_mfma_f32_16x16x32_bf16 v[36:39], v[144:147], v[188:191], v[36:39]
	v_mfma_f32_16x16x32_bf16 v[24:27], v[136:139], v[184:187], v[24:27]
	v_mfma_f32_16x16x32_bf16 v[20:23], v[144:147], v[184:187], v[20:23]
	v_mfma_f32_16x16x32_bf16 v[8:11], v[136:139], v[180:183], v[8:11]
	v_mfma_f32_16x16x32_bf16 v[4:7], v[144:147], v[180:183], v[2:5]
	s_branch .LBB0_520
